# prologue folded-F-weight items: six serialized tile loads (load, wait, LDS write per trip) issued back to back and waited once
# speedup vs baseline: 1.0030x; 1.0007x over previous
; __device__ __forceinline__ void prologue(const Args& A, LAS unsigned char* lds, int vcu, int G, const int tid) {
;     ...
;             for (int i = tid; i < 4096; i += 512) { const int kk = i >> 6, d = i & 63; wt[kk * 65 + d] = A.in[I_WIN][(size_t)(k0 + kk) * 2560 + 2304 + g * 64 + d]; }
.LBB0_131:
	s_waitcnt lgkmcnt(0)
	v_ashrrev_i32_e32 v6, 6, v2
	v_mov_b64_e32 v[4:5], s[10:11]
	v_add_u32_e32 v7, s1, v6
	s_lshl_b32 s72, s53, 2
	v_mad_i64_i32 v[4:5], s[46:47], v7, s36, v[4:5]
	v_mov_b32_e32 v79, v3
	v_lshl_add_u64 v[4:5], v[4:5], 0, s[72:73]
	v_lshl_add_u64 v[4:5], v[4:5], 0, v[78:79]
	v_add_co_u32_e32 v4, vcc, 0x2000, v4
	s_nop 1
	v_addc_co_u32_e32 v5, vcc, 0, v5, vcc
	global_load_dword v201, v[4:5], off offset:1024
	v_mad_u64_u32 v[208:209], s[46:47], v6, s37, v[50:51]
	v_add_u32_e32 v2, 0x200, v2
	v_ashrrev_i32_e32 v6, 6, v2
	v_mov_b64_e32 v[4:5], s[10:11]
	v_add_u32_e32 v7, s1, v6
	s_lshl_b32 s72, s53, 2
	v_mad_i64_i32 v[4:5], s[46:47], v7, s36, v[4:5]
	v_mov_b32_e32 v79, v3
	v_lshl_add_u64 v[4:5], v[4:5], 0, s[72:73]
	v_lshl_add_u64 v[4:5], v[4:5], 0, v[78:79]
	v_add_co_u32_e32 v4, vcc, 0x2000, v4
	s_nop 1
	v_addc_co_u32_e32 v5, vcc, 0, v5, vcc
	global_load_dword v202, v[4:5], off offset:1024
	v_mad_u64_u32 v[210:211], s[46:47], v6, s37, v[50:51]
	v_add_u32_e32 v2, 0x200, v2
	v_ashrrev_i32_e32 v6, 6, v2
	v_mov_b64_e32 v[4:5], s[10:11]
	v_add_u32_e32 v7, s1, v6
	s_lshl_b32 s72, s53, 2
	v_mad_i64_i32 v[4:5], s[46:47], v7, s36, v[4:5]
	v_mov_b32_e32 v79, v3
	v_lshl_add_u64 v[4:5], v[4:5], 0, s[72:73]
	v_lshl_add_u64 v[4:5], v[4:5], 0, v[78:79]
	v_add_co_u32_e32 v4, vcc, 0x2000, v4
	s_nop 1
	v_addc_co_u32_e32 v5, vcc, 0, v5, vcc
	global_load_dword v203, v[4:5], off offset:1024
	v_mad_u64_u32 v[212:213], s[46:47], v6, s37, v[50:51]
	v_add_u32_e32 v2, 0x200, v2
	v_ashrrev_i32_e32 v6, 6, v2
	v_mov_b64_e32 v[4:5], s[10:11]
	v_add_u32_e32 v7, s1, v6
	s_lshl_b32 s72, s53, 2
	v_mad_i64_i32 v[4:5], s[46:47], v7, s36, v[4:5]
	v_mov_b32_e32 v79, v3
	v_lshl_add_u64 v[4:5], v[4:5], 0, s[72:73]
	v_lshl_add_u64 v[4:5], v[4:5], 0, v[78:79]
	v_add_co_u32_e32 v4, vcc, 0x2000, v4
	s_nop 1
	v_addc_co_u32_e32 v5, vcc, 0, v5, vcc
	global_load_dword v204, v[4:5], off offset:1024
	v_mad_u64_u32 v[214:215], s[46:47], v6, s37, v[50:51]
	v_add_u32_e32 v2, 0x200, v2
	v_ashrrev_i32_e32 v6, 6, v2
	v_mov_b64_e32 v[4:5], s[10:11]
	v_add_u32_e32 v7, s1, v6
	s_lshl_b32 s72, s53, 2
	v_mad_i64_i32 v[4:5], s[46:47], v7, s36, v[4:5]
	v_mov_b32_e32 v79, v3
	v_lshl_add_u64 v[4:5], v[4:5], 0, s[72:73]
	v_lshl_add_u64 v[4:5], v[4:5], 0, v[78:79]
	v_add_co_u32_e32 v4, vcc, 0x2000, v4
	s_nop 1
	v_addc_co_u32_e32 v5, vcc, 0, v5, vcc
	global_load_dword v205, v[4:5], off offset:1024
	v_mad_u64_u32 v[216:217], s[46:47], v6, s37, v[50:51]
	v_add_u32_e32 v2, 0x200, v2
	v_ashrrev_i32_e32 v6, 6, v2
	v_mov_b64_e32 v[4:5], s[10:11]
	v_add_u32_e32 v7, s1, v6
	s_lshl_b32 s72, s53, 2
	v_mad_i64_i32 v[4:5], s[46:47], v7, s36, v[4:5]
	v_mov_b32_e32 v79, v3
	v_lshl_add_u64 v[4:5], v[4:5], 0, s[72:73]
	v_lshl_add_u64 v[4:5], v[4:5], 0, v[78:79]
	v_add_co_u32_e32 v4, vcc, 0x2000, v4
	s_nop 1
	v_addc_co_u32_e32 v5, vcc, 0, v5, vcc
	global_load_dword v206, v[4:5], off offset:1024
	v_mad_u64_u32 v[218:219], s[46:47], v6, s37, v[50:51]
	v_add_u32_e32 v2, 0x200, v2
	s_movk_i32 s46, 0xdff
	s_waitcnt vmcnt(5)
	ds_write_b32 v208, v201
	s_waitcnt vmcnt(4)
	ds_write_b32 v210, v202
	s_waitcnt vmcnt(3)
	ds_write_b32 v212, v203
	s_waitcnt vmcnt(2)
	ds_write_b32 v214, v204
	s_waitcnt vmcnt(1)
	ds_write_b32 v216, v205
	s_waitcnt vmcnt(0)
	ds_write_b32 v218, v206
	s_mov_b64 s[44:45], exec
